# phase-2 queue lookahead extended to conversion-group units (ticket requested during the group's last store phase)
# speedup vs baseline: 1.0015x; 1.0015x over previous
.LBB0_269:
	s_barrier
	s_mov_b64 s[0:1], exec
	v_readlane_b32 s4, v197, 0
	v_readlane_b32 s5, v197, 1
	s_and_b64 s[4:5], s[0:1], s[4:5]
	s_mov_b64 exec, s[4:5]
	s_cbranch_execz .LBB0_273
	s_mov_b64 s[6:7], exec
	v_mbcnt_lo_u32_b32 v2, s6, 0
	v_mbcnt_hi_u32_b32 v2, s7, v2
	v_cmp_eq_u32_e32 vcc, 0, v2
	s_and_saveexec_b64 s[4:5], vcc
	s_cbranch_execz .LBB0_272
	s_bcnt1_i32_b64 s6, s[6:7]
	v_mov_b32_e32 v3, s6
	s_cmp_lg_u32 s99, 0
	s_cbranch_scc1 .Ldq_have
	global_atomic_add v3, v99, v3, s[92:93] offset:8 sc0
	s_branch .LBB0_272
.Ldq_have:
	s_cmp_eq_u32 s99, 2
	s_cbranch_scc0 .Ldq_have_ready
	s_waitcnt vmcnt(0)

.LBB0_288:
	s_barrier
	s_waitcnt vmcnt(0)
	ds_write2_b32 v69, v2, v3 offset1:1
	ds_write2_b32 v69, v4, v5 offset0:2 offset1:3
	s_waitcnt vmcnt(6)
	ds_write2_b32 v69, v6, v7 offset0:4 offset1:5
	ds_write2_b32 v69, v8, v9 offset0:6 offset1:7
	v_add_u32_e32 v2, 0x4100, v69
	s_waitcnt vmcnt(5)
	ds_write2_b32 v2, v10, v11 offset1:1
	v_add_u32_e32 v2, 0x4108, v69
	ds_write2_b32 v2, v12, v13 offset1:1
	v_add_u32_e32 v2, 0x4110, v69
	s_waitcnt vmcnt(4)
	ds_write2_b32 v2, v14, v15 offset1:1
	v_add_u32_e32 v2, 0x4118, v69
	ds_write2_b32 v2, v16, v17 offset1:1
	v_add_u32_e32 v2, 0x8200, v69
	s_waitcnt vmcnt(3)
	ds_write2_b32 v2, v18, v19 offset1:1
	v_add_u32_e32 v2, 0x8208, v69
	ds_write2_b32 v2, v20, v21 offset1:1
	v_add_u32_e32 v2, 0x8210, v69
	s_waitcnt vmcnt(2)
	ds_write2_b32 v2, v22, v23 offset1:1
	v_add_u32_e32 v2, 0x8218, v69
	ds_write2_b32 v2, v24, v25 offset1:1
	v_add_u32_e32 v2, 0xc300, v69
	s_waitcnt vmcnt(1)
	ds_write2_b32 v2, v26, v27 offset1:1
	v_add_u32_e32 v2, 0xc308, v69
	ds_write2_b32 v2, v28, v29 offset1:1
	v_add_u32_e32 v2, 0xc310, v69
	s_waitcnt vmcnt(0)
	ds_write2_b32 v2, v30, v31 offset1:1
	v_add_u32_e32 v2, 0xc318, v69
	ds_write2_b32 v2, v32, v33 offset1:1
	s_waitcnt lgkmcnt(0)
	s_barrier
	ds_read2_b32 v[2:3], v76 offset1:65
	ds_read2_b32 v[4:5], v76 offset0:130 offset1:195
	v_add_u32_e32 v8, 0x400, v76
	ds_read2_b32 v[6:7], v8 offset0:4 offset1:69
	ds_read2_b32 v[8:9], v8 offset0:134 offset1:199
	v_add_u32_e32 v10, 0x4400, v76
	s_waitcnt lgkmcnt(3)
	v_cvt_pk_bf16_f32 v2, v2, v3
	s_waitcnt lgkmcnt(2)
	v_cvt_pk_bf16_f32 v3, v4, v5
	s_waitcnt lgkmcnt(1)
	v_cvt_pk_bf16_f32 v4, v6, v7
	v_add_u32_e32 v6, 0x4000, v76
	v_add_u32_e32 v12, 0x4600, v76
	s_waitcnt lgkmcnt(0)
	v_cvt_pk_bf16_f32 v5, v8, v9
	ds_read2_b32 v[6:7], v6 offset0:64 offset1:129
	v_add_u32_e32 v8, 0x4200, v76
	ds_read2_b32 v[10:11], v10 offset0:68 offset1:133
	ds_read2_b32 v[12:13], v12 offset0:70 offset1:135
	ds_read2_b32 v[8:9], v8 offset0:66 offset1:131
	global_store_dwordx4 v[72:73], v[2:5], off
	s_add_i32 s64, s64, 1
	s_cmp_ge_u32 s72, s33
	s_cbranch_scc0 .Ldq_cvt_skip
	s_mov_b64 s[6:7], exec
	v_readlane_b32 s8, v197, 0
	v_readlane_b32 s9, v197, 1
	s_and_b64 s[8:9], s[6:7], s[8:9]
	s_mov_b64 exec, s[8:9]
	s_cbranch_execz .Ldq_cvt_m
	v_mov_b32_e32 v251, 0
	v_mov_b32_e32 v252, 1
	global_atomic_add v250, v251, v252, s[92:93] offset:8 sc0
.Ldq_cvt_m:
	s_mov_b64 exec, s[6:7]
	s_mov_b32 s99, 2
.Ldq_cvt_skip:
	s_cmp_ge_u32 s72, s33
	s_waitcnt lgkmcnt(3)
	v_cvt_pk_bf16_f32 v2, v6, v7
	s_waitcnt lgkmcnt(2)
	v_cvt_pk_bf16_f32 v4, v10, v11
	s_waitcnt lgkmcnt(1)
	v_cvt_pk_bf16_f32 v5, v12, v13
	v_add_u32_e32 v6, 0x8000, v76
	v_add_u32_e32 v10, 0x8400, v76
	v_add_u32_e32 v12, 0x8800, v76
	s_waitcnt lgkmcnt(0)
	v_cvt_pk_bf16_f32 v3, v8, v9
	ds_read2_b32 v[6:7], v6 offset0:128 offset1:193
	ds_read2_b32 v[8:9], v10 offset0:2 offset1:67
	ds_read2_b32 v[10:11], v10 offset0:132 offset1:197
	ds_read2_b32 v[12:13], v12 offset0:6 offset1:71
	global_store_dwordx4 v[72:73], v[2:5], off offset:128
	v_mov_b32_e32 v14, v46
	v_mov_b32_e32 v15, v47
	s_waitcnt lgkmcnt(3)
	v_cvt_pk_bf16_f32 v2, v6, v7
	s_waitcnt lgkmcnt(2)
	v_cvt_pk_bf16_f32 v3, v8, v9
	s_waitcnt lgkmcnt(1)
	v_cvt_pk_bf16_f32 v4, v10, v11
	s_waitcnt lgkmcnt(0)
	v_cvt_pk_bf16_f32 v5, v12, v13
	v_add_u32_e32 v6, 0xc200, v76
	v_add_u32_e32 v8, 0xc400, v76
	v_add_u32_e32 v10, 0xc600, v76
	v_add_u32_e32 v12, 0xc800, v76
	ds_read2_b32 v[6:7], v6 offset0:64 offset1:129
	ds_read2_b32 v[8:9], v8 offset0:66 offset1:131
	ds_read2_b32 v[10:11], v10 offset0:68 offset1:133
	ds_read2_b32 v[12:13], v12 offset0:70 offset1:135
	global_store_dwordx4 v[72:73], v[2:5], off offset:256
	v_mov_b32_e32 v16, v48
	v_mov_b32_e32 v17, v49
	s_waitcnt lgkmcnt(3)
	v_cvt_pk_bf16_f32 v2, v6, v7
	s_waitcnt lgkmcnt(2)
	v_cvt_pk_bf16_f32 v3, v8, v9
	s_waitcnt lgkmcnt(1)
	v_cvt_pk_bf16_f32 v4, v10, v11
	s_waitcnt lgkmcnt(0)
	v_cvt_pk_bf16_f32 v5, v12, v13
	global_store_dwordx4 v[72:73], v[2:5], off offset:384
	v_mov_b64_e32 v[72:73], v[74:75]
	v_mov_b32_e32 v6, v34
	v_mov_b32_e32 v2, v38
	v_mov_b32_e32 v3, v39
	v_mov_b32_e32 v4, v40
	v_mov_b32_e32 v5, v41
	v_mov_b32_e32 v7, v35
	v_mov_b32_e32 v8, v36
	v_mov_b32_e32 v9, v37
	v_mov_b32_e32 v10, v42
	v_mov_b32_e32 v11, v43
	v_mov_b32_e32 v12, v44
	v_mov_b32_e32 v13, v45
	v_mov_b32_e32 v18, v50
	v_mov_b32_e32 v19, v51
	v_mov_b32_e32 v20, v52
	v_mov_b32_e32 v21, v53
	v_mov_b32_e32 v22, v54
	v_mov_b32_e32 v23, v55
	v_mov_b32_e32 v24, v56
	v_mov_b32_e32 v25, v57
	v_mov_b32_e32 v26, v58
	v_mov_b32_e32 v27, v59
	v_mov_b32_e32 v28, v60
	v_mov_b32_e32 v29, v61
	v_mov_b32_e32 v30, v62
	v_mov_b32_e32 v31, v63
	v_mov_b32_e32 v32, v64
	v_mov_b32_e32 v33, v65
	s_cbranch_scc1 .LBB0_294
